# down-GEMM residual epilogue: touch the second half-tile's residual lines (discarded loads) together with the first half's loads so the later real loads hit cache
# baseline (speedup 1.0000x reference)
.LBB0_1200:
	s_mov_b32 s100, 0x40000
	s_mov_b32 s101, 0
	s_ashr_i32 s29, s28, 31
	v_lshl_or_b32 v180, s50, 8, v205
	s_lshl_b64 s[2:3], s[28:29], 8
	v_lshl_add_u64 v[182:183], s[2:3], 0, v[164:165]
	v_ashrrev_i32_e32 v181, 31, v180
	v_lshl_add_u64 v[184:185], v[180:181], 1, s[16:17]
	v_lshlrev_b64 v[200:201], 11, v[182:183]
	v_or_b32_e32 v196, 16, v182
	v_mov_b32_e32 v197, v183
	v_lshl_add_u64 v[130:131], v[184:185], 0, v[200:201]
	v_lshlrev_b64 v[194:195], 11, v[196:197]
	v_or_b32_e32 v192, 32, v182
	v_mov_b32_e32 v193, v183
	global_load_dwordx4 v[208:211], v[130:131], off
	global_load_dwordx4 v[154:157], v[130:131], off offset:256
	v_lshl_add_u64 v[246:247], v[130:131], 0, s[100:101]
	global_load_dwordx4 v[248:251], v[246:247], off
	global_load_dwordx4 v[248:251], v[246:247], off offset:256
	v_lshl_add_u64 v[130:131], v[184:185], 0, v[194:195]
	v_lshlrev_b64 v[190:191], 11, v[192:193]
	v_or_b32_e32 v188, 48, v182
	v_mov_b32_e32 v189, v183
	global_load_dwordx4 v[150:153], v[130:131], off
	global_load_dwordx4 v[146:149], v[130:131], off offset:256
	v_lshl_add_u64 v[246:247], v[130:131], 0, s[100:101]
	global_load_dwordx4 v[248:251], v[246:247], off
	global_load_dwordx4 v[248:251], v[246:247], off offset:256
	v_lshl_add_u64 v[130:131], v[184:185], 0, v[190:191]
	v_lshlrev_b64 v[186:187], 11, v[188:189]
	global_load_dwordx4 v[142:145], v[130:131], off
	global_load_dwordx4 v[138:141], v[130:131], off offset:256
	v_lshl_add_u64 v[246:247], v[130:131], 0, s[100:101]
	global_load_dwordx4 v[248:251], v[246:247], off
	global_load_dwordx4 v[248:251], v[246:247], off offset:256
	v_lshl_add_u64 v[130:131], v[184:185], 0, v[186:187]
	global_load_dwordx4 v[134:137], v[130:131], off
	v_lshl_add_u64 v[246:247], v[130:131], 0, s[100:101]
	global_load_dwordx4 v[130:133], v[130:131], off offset:256
	global_load_dwordx4 v[248:251], v[246:247], off
	global_load_dwordx4 v[248:251], v[246:247], off offset:256
	v_cndmask_b32_e64 v198, 0, 1, s[22:23]
	v_cmp_ne_u32_e64 s[8:9], 1, v198
	v_lshlrev_b64 v[198:199], 12, v[182:183]
	v_lshl_add_u64 v[198:199], s[12:13], 0, v[198:199]
	s_andn2_b64 vcc, exec, s[22:23]
	s_waitcnt vmcnt(0)
	v_lshlrev_b32_e32 v202, 16, v208
	v_and_b32_e32 v203, 0xffff0000, v208
	v_lshlrev_b32_e32 v208, 16, v209
	v_and_b32_e32 v209, 0xffff0000, v209
	v_lshlrev_b32_e32 v212, 16, v210
	v_and_b32_e32 v213, 0xffff0000, v210
	v_lshlrev_b32_e32 v210, 16, v211
	v_and_b32_e32 v211, 0xffff0000, v211
	v_pk_fma_f32 v[128:129], v[128:129], 0.5, v[208:209] op_sel_hi:[1,0,1]
	v_pk_fma_f32 v[126:127], v[126:127], 0.5, v[202:203] op_sel_hi:[1,0,1]
	v_pk_fma_f32 v[124:125], v[124:125], 0.5, v[210:211] op_sel_hi:[1,0,1]
	v_pk_fma_f32 v[122:123], v[122:123], 0.5, v[212:213] op_sel_hi:[1,0,1]
	v_lshl_add_u64 v[202:203], v[180:181], 2, v[198:199]
	s_cbranch_vccnz .LBB0_1202
	s_mov_b64 s[30:31], 0
	global_store_dwordx4 v[202:203], v[126:129], off
	global_store_dwordx4 v[202:203], v[122:125], off offset:16
	s_branch .LBB0_1203
